# v27 plus DPP wave reductions in norm/final row loops and attention unit prologue issuing tile-1 K/V loads with tile-0
# baseline (speedup 1.0000x reference)
; DI void st4(u16* p, float a, float b, float c, float d) { u32x2 w = {cvtpk(a, b), cvtpk(c, d)}; *(u32x2*)p = w; }
; #define ROW_LOOP(row, NROWS, BID, NB, WID) \
;   for (int it_ = 0, row = ((NB) == 256 ? ((((BID) & 7)) << 8) + (((BID) >> 3) << 3) + (WID) : (BID) * 8 + (WID)); row < (NROWS); \
;        ++it_, row = ((NB) == 256 ? ((((BID) & 7) + 8 * it_) << 8) + (((BID) >> 3) << 3) + (WID) : (BID) * 8 + (WID) + it_ * (NB) * 8))
; DI float wsum(float v) {
; #pragma unroll
;   for (int o = 32; o; o >>= 1) v += __shfl_xor(v, o);
;   return v;
; }
; template <bool XBF>
; DI void norm_mod_phase(const void* __restrict__ xv, u16* __restrict__ h, const float* __restrict__ gvec, const float* __restrict__ modl, int seq0, int sh_off, int sc_off, int nrows, u16* __restrict__ hdst) {
;     ...
;   ROW_LOOP(row, nrows, bid_, nb_, wid) {
;     const float* mr = modl + (size_t)(seq0 + (row >> 12)) * 6144;
;     f32x4 v[4]; float ss = 0.f;
;     if constexpr (!XBF) {
;       const f32x4* xr = (const f32x4*)((const float*)xv + (size_t)row * 1024);
; #pragma unroll
;       for (int i = 0; i < 4; ++i) v[i] = xr[lane + 64 * i];
;     } else {
;       const u32x2* xr = (const u32x2*)((const u16*)xv + (size_t)row * 1024);
; #pragma unroll
;       for (int i = 0; i < 4; ++i) { const u32x2 w = xr[lane + 64 * i]; v[i] = f32x4{__uint_as_float(w[0] << 16), __uint_as_float(w[0] & 0xffff0000u), __uint_as_float(w[1] << 16), __uint_as_float(w[1] & 0xffff0000u)}; }
;     }
; #pragma unroll
;     for (int i = 0; i < 4; ++i) ss += v[i][0] * v[i][0] + v[i][1] * v[i][1] + v[i][2] * v[i][2] + v[i][3] * v[i][3];
;     ss = wsum(ss);
;     const float rstd = rsqrtf(ss * (1.f / 1024.f) + EPS);
; #pragma unroll
;     for (int i = 0; i < 4; ++i) {
;       const int col = (lane + 64 * i) * 4;
;       const f32x4 g = *(const f32x4*)(gvec + col), sc = *(const f32x4*)(mr + sc_off + col), sh = *(const f32x4*)(mr + sh_off + col);
;       float o[4];
; #pragma unroll
;       for (int q = 0; q < 4; ++q) o[q] = v[i][q] * rstd * g[q] * (1.f + sc[q]) + sh[q];
;       st4(h + (size_t)row * 1024 + col, o[0], o[1], o[2], o[3]);
;     }
.Lfn_A_top:
	v_lshlrev_b32_e32 v86, 16, v76
	v_and_b32_e32 v84, 0xffff0000, v76
	v_lshlrev_b32_e32 v88, 16, v77
	v_and_b32_e32 v90, 0xffff0000, v77
	v_lshlrev_b32_e32 v87, 16, v78
	v_and_b32_e32 v85, 0xffff0000, v78
	v_lshlrev_b32_e32 v89, 16, v79
	v_and_b32_e32 v91, 0xffff0000, v79
	v_lshlrev_b32_e32 v94, 16, v80
	v_and_b32_e32 v92, 0xffff0000, v80
	v_lshlrev_b32_e32 v96, 16, v81
	v_and_b32_e32 v98, 0xffff0000, v81
	v_lshlrev_b32_e32 v95, 16, v82
	v_and_b32_e32 v93, 0xffff0000, v82
	v_lshlrev_b32_e32 v97, 16, v83
	v_and_b32_e32 v99, 0xffff0000, v83
	s_lshr_b32 s78, s70, 12
	s_add_i32 s78, s78, s0
	s_mul_i32 s78, s78, s81
	s_add_u32 s74, s12, s78
	s_addc_u32 s75, s13, 0
	s_add_u32 s76, s74, 0x3000
	s_addc_u32 s77, s75, 0
	s_add_u32 s74, s74, 0x4000
	s_addc_u32 s75, s75, 0
	global_load_dwordx4 v[100:103], v128, s[74:75]
	global_load_dwordx4 v[104:107], v128, s[74:75] offset:1024
	global_load_dwordx4 v[108:111], v128, s[74:75] offset:2048
	global_load_dwordx4 v[112:115], v128, s[74:75] offset:3072
	global_load_dwordx4 v[20:23], v128, s[76:77]
	global_load_dwordx4 v[24:27], v128, s[76:77] offset:1024
	global_load_dwordx4 v[28:31], v128, s[76:77] offset:2048
	global_load_dwordx4 v[32:35], v128, s[76:77] offset:3072
	s_add_i32 s71, s70, 0x800
	s_cmp_lt_i32 s71, 0x4000
	s_cselect_b32 s78, s71, s70
	s_lshl_b32 s72, s78, 11
	v_lshl_add_u64 v[6:7], v[10:11], 0, s[72:73]
	global_load_dwordx2 v[76:77], v[6:7], off
	global_load_dwordx2 v[78:79], v[6:7], off offset:512
	global_load_dwordx2 v[80:81], v[6:7], off offset:1024
	global_load_dwordx2 v[82:83], v[6:7], off offset:1536
	v_pk_mul_f32 v[36:37], v[84:85], v[84:85]
	v_pk_fma_f32 v[36:37], v[86:87], v[86:87], v[36:37]
	v_pk_fma_f32 v[36:37], v[88:89], v[88:89], v[36:37]
	v_pk_fma_f32 v[36:37], v[90:91], v[90:91], v[36:37]
	v_pk_mul_f32 v[38:39], v[92:93], v[92:93]
	v_pk_fma_f32 v[38:39], v[94:95], v[94:95], v[38:39]
	v_pk_fma_f32 v[38:39], v[96:97], v[96:97], v[38:39]
	v_pk_fma_f32 v[38:39], v[98:99], v[98:99], v[38:39]
	v_add_f32_e32 v17, v36, v37
	v_add_f32_e32 v17, v17, v38
	v_add_f32_e32 v17, v17, v39
	s_lshl_b32 s72, s70, 11
	v_lshl_add_u64 v[40:41], v[12:13], 0, s[72:73]
	s_nop 0
	v_add_f32_dpp v17, v17, v17 row_shr:1 row_mask:0xf bank_mask:0xf bound_ctrl:0
	s_nop 1
	v_add_f32_dpp v17, v17, v17 row_shr:2 row_mask:0xf bank_mask:0xf bound_ctrl:0
	s_nop 1
	v_add_f32_dpp v17, v17, v17 row_shr:4 row_mask:0xf bank_mask:0xf bound_ctrl:0
	s_nop 1
	v_add_f32_dpp v17, v17, v17 row_shr:8 row_mask:0xf bank_mask:0xf bound_ctrl:0
	s_nop 1
	v_add_f32_dpp v17, v17, v17 row_bcast:15 row_mask:0xa bank_mask:0xf
	s_nop 1
	v_add_f32_dpp v17, v17, v17 row_bcast:31 row_mask:0xc bank_mask:0xf
	s_nop 1
	v_readlane_b32 s72, v17, 63
	s_nop 1
	v_mov_b32_e32 v15, s72
	v_fmamk_f32 v15, v15, 0x3a800000, v142
	v_cmp_gt_f32_e32 vcc, s79, v15
	v_mul_f32_e32 v17, 0x4b800000, v15
	s_nop 1
	v_cndmask_b32_e32 v15, v15, v17, vcc
	v_rsq_f32_e32 v15, v15
	s_nop 0
	v_mul_f32_e32 v17, 0x45800000, v15
	v_cndmask_b32_e32 v49, v15, v17, vcc
	s_waitcnt vmcnt(4)
	v_mul_f32_e32 v50, v49, v86
	v_mul_f32_e32 v51, v49, v84
	v_mul_f32_e32 v52, v49, v88
	v_mul_f32_e32 v53, v49, v90
	v_mul_f32_e32 v50, v0, v50
	v_mul_f32_e32 v51, v1, v51
	v_mul_f32_e32 v52, v2, v52
	v_mul_f32_e32 v53, v3, v53
	v_add_f32_e32 v100, 1.0, v100
	v_add_f32_e32 v101, 1.0, v101
	v_add_f32_e32 v102, 1.0, v102
	v_add_f32_e32 v103, 1.0, v103
	v_fma_f32 v50, v100, v50, v20
	v_fma_f32 v51, v101, v51, v21
	v_fma_f32 v52, v102, v52, v22
	v_fma_f32 v53, v103, v53, v23
	v_cvt_pk_bf16_f32 v54, v50, v51
	v_cvt_pk_bf16_f32 v55, v52, v53
	global_store_dwordx2 v[40:41], v[54:55], off
	v_mul_f32_e32 v50, v49, v87
	v_mul_f32_e32 v51, v49, v85
	v_mul_f32_e32 v52, v49, v89
	v_mul_f32_e32 v53, v49, v91
	v_mul_f32_e32 v50, v64, v50
	v_mul_f32_e32 v51, v65, v51
	v_mul_f32_e32 v52, v66, v52
	v_mul_f32_e32 v53, v67, v53
	v_add_f32_e32 v104, 1.0, v104
	v_add_f32_e32 v105, 1.0, v105
	v_add_f32_e32 v106, 1.0, v106
	v_add_f32_e32 v107, 1.0, v107
	v_fma_f32 v50, v104, v50, v24
	v_fma_f32 v51, v105, v51, v25
	v_fma_f32 v52, v106, v52, v26
	v_fma_f32 v53, v107, v53, v27
	v_cvt_pk_bf16_f32 v56, v50, v51
	v_cvt_pk_bf16_f32 v57, v52, v53
	global_store_dwordx2 v[40:41], v[56:57], off offset:512
	v_mul_f32_e32 v50, v49, v94
	v_mul_f32_e32 v51, v49, v92
	v_mul_f32_e32 v52, v49, v96
	v_mul_f32_e32 v53, v49, v98
	v_mul_f32_e32 v50, v68, v50
	v_mul_f32_e32 v51, v69, v51
	v_mul_f32_e32 v52, v70, v52
	v_mul_f32_e32 v53, v71, v53
	v_add_f32_e32 v108, 1.0, v108
	v_add_f32_e32 v109, 1.0, v109
	v_add_f32_e32 v110, 1.0, v110
	v_add_f32_e32 v111, 1.0, v111
	v_fma_f32 v50, v108, v50, v28
	v_fma_f32 v51, v109, v51, v29
	v_fma_f32 v52, v110, v52, v30
	v_fma_f32 v53, v111, v53, v31
	v_cvt_pk_bf16_f32 v54, v50, v51
	v_cvt_pk_bf16_f32 v55, v52, v53
	global_store_dwordx2 v[40:41], v[54:55], off offset:1024
	v_mul_f32_e32 v50, v49, v95
	v_mul_f32_e32 v51, v49, v93
	v_mul_f32_e32 v52, v49, v97
	v_mul_f32_e32 v53, v49, v99
	v_mul_f32_e32 v50, v72, v50
	v_mul_f32_e32 v51, v73, v51
	v_mul_f32_e32 v52, v74, v52
	v_mul_f32_e32 v53, v75, v53
	v_add_f32_e32 v112, 1.0, v112
	v_add_f32_e32 v113, 1.0, v113
	v_add_f32_e32 v114, 1.0, v114
	v_add_f32_e32 v115, 1.0, v115
	v_fma_f32 v50, v112, v50, v32
	v_fma_f32 v51, v113, v51, v33
	v_fma_f32 v52, v114, v52, v34
	v_fma_f32 v53, v115, v53, v35
	v_cvt_pk_bf16_f32 v56, v50, v51
	v_cvt_pk_bf16_f32 v57, v52, v53
	global_store_dwordx2 v[40:41], v[56:57], off offset:1536
	s_mov_b32 s70, s71
	s_cmp_lt_i32 s71, 0x4000
	s_waitcnt vmcnt(4)
	s_cbranch_scc1 .Lfn_A_top
	s_branch .LBB0_731

; DI void st4(u16* p, float a, float b, float c, float d) { u32x2 w = {cvtpk(a, b), cvtpk(c, d)}; *(u32x2*)p = w; }
; #define ROW_LOOP(row, NROWS, BID, NB, WID) \
;   for (int it_ = 0, row = ((NB) == 256 ? ((((BID) & 7)) << 8) + (((BID) >> 3) << 3) + (WID) : (BID) * 8 + (WID)); row < (NROWS); \
;        ++it_, row = ((NB) == 256 ? ((((BID) & 7) + 8 * it_) << 8) + (((BID) >> 3) << 3) + (WID) : (BID) * 8 + (WID) + it_ * (NB) * 8))
; DI float wsum(float v) {
; #pragma unroll
;   for (int o = 32; o; o >>= 1) v += __shfl_xor(v, o);
;   return v;
; }
; template <bool XBF>
; DI void norm_mod_phase(const void* __restrict__ xv, u16* __restrict__ h, const float* __restrict__ gvec, const float* __restrict__ modl, int seq0, int sh_off, int sc_off, int nrows, u16* __restrict__ hdst) {
;     ...
;   ROW_LOOP(row, nrows, bid_, nb_, wid) {
;     const float* mr = modl + (size_t)(seq0 + (row >> 12)) * 6144;
;     f32x4 v[4]; float ss = 0.f;
;     if constexpr (!XBF) {
;       const f32x4* xr = (const f32x4*)((const float*)xv + (size_t)row * 1024);
; #pragma unroll
;       for (int i = 0; i < 4; ++i) v[i] = xr[lane + 64 * i];
;     } else {
;       const u32x2* xr = (const u32x2*)((const u16*)xv + (size_t)row * 1024);
; #pragma unroll
;       for (int i = 0; i < 4; ++i) { const u32x2 w = xr[lane + 64 * i]; v[i] = f32x4{__uint_as_float(w[0] << 16), __uint_as_float(w[0] & 0xffff0000u), __uint_as_float(w[1] << 16), __uint_as_float(w[1] & 0xffff0000u)}; }
;     }
; #pragma unroll
;     for (int i = 0; i < 4; ++i) ss += v[i][0] * v[i][0] + v[i][1] * v[i][1] + v[i][2] * v[i][2] + v[i][3] * v[i][3];
;     ss = wsum(ss);
;     const float rstd = rsqrtf(ss * (1.f / 1024.f) + EPS);
; #pragma unroll
;     for (int i = 0; i < 4; ++i) {
;       const int col = (lane + 64 * i) * 4;
;       const f32x4 g = *(const f32x4*)(gvec + col), sc = *(const f32x4*)(mr + sc_off + col), sh = *(const f32x4*)(mr + sh_off + col);
;       float o[4];
; #pragma unroll
;       for (int q = 0; q < 4; ++q) o[q] = v[i][q] * rstd * g[q] * (1.f + sc[q]) + sh[q];
;       st4(h + (size_t)row * 1024 + col, o[0], o[1], o[2], o[3]);
;     }
.Lfn_D_top:
	v_lshlrev_b32_e32 v86, 16, v76
	v_and_b32_e32 v84, 0xffff0000, v76
	v_lshlrev_b32_e32 v88, 16, v77
	v_and_b32_e32 v90, 0xffff0000, v77
	v_lshlrev_b32_e32 v87, 16, v78
	v_and_b32_e32 v85, 0xffff0000, v78
	v_lshlrev_b32_e32 v89, 16, v79
	v_and_b32_e32 v91, 0xffff0000, v79
	v_lshlrev_b32_e32 v94, 16, v80
	v_and_b32_e32 v92, 0xffff0000, v80
	v_lshlrev_b32_e32 v96, 16, v81
	v_and_b32_e32 v98, 0xffff0000, v81
	v_lshlrev_b32_e32 v95, 16, v82
	v_and_b32_e32 v93, 0xffff0000, v82
	v_lshlrev_b32_e32 v97, 16, v83
	v_and_b32_e32 v99, 0xffff0000, v83
	s_lshr_b32 s16, s1, 12
	s_mul_i32 s16, s16, 0x6000
	s_add_u32 s16, s10, s16
	s_addc_u32 s17, s11, 0
	global_load_dwordx4 v[100:103], v53, s[16:17]
	global_load_dwordx4 v[104:107], v53, s[16:17] offset:1024
	global_load_dwordx4 v[108:111], v53, s[16:17] offset:2048
	global_load_dwordx4 v[112:115], v53, s[16:17] offset:3072
	global_load_dwordx4 v[24:27], v128, s[16:17]
	global_load_dwordx4 v[28:31], v128, s[16:17] offset:1024
	global_load_dwordx4 v[32:35], v128, s[16:17] offset:2048
	global_load_dwordx4 v[36:39], v128, s[16:17] offset:3072
	s_add_i32 s2, s1, 0x800
	s_cmp_lt_i32 s2, 0x8000
	s_cselect_b32 s12, s2, s1
	s_lshl_b32 s12, s12, 11
	v_lshl_add_u64 v[6:7], v[14:15], 0, s[12:13]
	global_load_dwordx2 v[76:77], v[6:7], off
	global_load_dwordx2 v[78:79], v[6:7], off offset:512
	global_load_dwordx2 v[80:81], v[6:7], off offset:1024
	global_load_dwordx2 v[82:83], v[6:7], off offset:1536
	v_pk_mul_f32 v[42:43], v[84:85], v[84:85]
	v_pk_fma_f32 v[42:43], v[86:87], v[86:87], v[42:43]
	v_pk_fma_f32 v[42:43], v[88:89], v[88:89], v[42:43]
	v_pk_fma_f32 v[42:43], v[90:91], v[90:91], v[42:43]
	v_pk_mul_f32 v[44:45], v[92:93], v[92:93]
	v_pk_fma_f32 v[44:45], v[94:95], v[94:95], v[44:45]
	v_pk_fma_f32 v[44:45], v[96:97], v[96:97], v[44:45]
	v_pk_fma_f32 v[44:45], v[98:99], v[98:99], v[44:45]
	v_add_f32_e32 v21, v42, v43
	v_add_f32_e32 v21, v21, v44
	v_add_f32_e32 v21, v21, v45
	s_lshl_b32 s12, s1, 11
	v_lshl_add_u64 v[40:41], v[16:17], 0, s[12:13]
	s_nop 0
	v_add_f32_dpp v21, v21, v21 row_shr:1 row_mask:0xf bank_mask:0xf bound_ctrl:0
	s_nop 1
	v_add_f32_dpp v21, v21, v21 row_shr:2 row_mask:0xf bank_mask:0xf bound_ctrl:0
	s_nop 1
	v_add_f32_dpp v21, v21, v21 row_shr:4 row_mask:0xf bank_mask:0xf bound_ctrl:0
	s_nop 1
	v_add_f32_dpp v21, v21, v21 row_shr:8 row_mask:0xf bank_mask:0xf bound_ctrl:0
	s_nop 1
	v_add_f32_dpp v21, v21, v21 row_bcast:15 row_mask:0xa bank_mask:0xf
	s_nop 1
	v_add_f32_dpp v21, v21, v21 row_bcast:31 row_mask:0xc bank_mask:0xf
	s_nop 1
	v_readlane_b32 s12, v21, 63
	s_nop 1
	v_mov_b32_e32 v19, s12
	v_fmamk_f32 v19, v19, 0x3a800000, v142
	v_cmp_gt_f32_e32 vcc, 0x800000, v19
	v_mul_f32_e32 v21, 0x4b800000, v19
	s_nop 1
	v_cndmask_b32_e32 v19, v19, v21, vcc
	v_rsq_f32_e32 v19, v19
	s_nop 0
	v_mul_f32_e32 v21, 0x45800000, v19
	v_cndmask_b32_e32 v23, v19, v21, vcc
	s_waitcnt vmcnt(4)
	v_mul_f32_e32 v54, v23, v86
	v_mul_f32_e32 v55, v23, v84
	v_mul_f32_e32 v56, v23, v88
	v_mul_f32_e32 v57, v23, v90
	v_mul_f32_e32 v54, v0, v54
	v_mul_f32_e32 v55, v1, v55
	v_mul_f32_e32 v56, v2, v56
	v_mul_f32_e32 v57, v3, v57
	v_add_f32_e32 v100, 1.0, v100
	v_add_f32_e32 v101, 1.0, v101
	v_add_f32_e32 v102, 1.0, v102
	v_add_f32_e32 v103, 1.0, v103
	v_fma_f32 v54, v100, v54, v24
	v_fma_f32 v55, v101, v55, v25
	v_fma_f32 v56, v102, v56, v26
	v_fma_f32 v57, v103, v57, v27
	v_cvt_pk_bf16_f32 v58, v54, v55
	v_cvt_pk_bf16_f32 v59, v56, v57
	global_store_dwordx2 v[40:41], v[58:59], off
	v_mul_f32_e32 v54, v23, v87
	v_mul_f32_e32 v55, v23, v85
	v_mul_f32_e32 v56, v23, v89
	v_mul_f32_e32 v57, v23, v91
	v_mul_f32_e32 v54, v64, v54
	v_mul_f32_e32 v55, v65, v55
	v_mul_f32_e32 v56, v66, v56
	v_mul_f32_e32 v57, v67, v57
	v_add_f32_e32 v104, 1.0, v104
	v_add_f32_e32 v105, 1.0, v105
	v_add_f32_e32 v106, 1.0, v106
	v_add_f32_e32 v107, 1.0, v107
	v_fma_f32 v54, v104, v54, v28
	v_fma_f32 v55, v105, v55, v29
	v_fma_f32 v56, v106, v56, v30
	v_fma_f32 v57, v107, v57, v31
	v_cvt_pk_bf16_f32 v60, v54, v55
	v_cvt_pk_bf16_f32 v61, v56, v57
	global_store_dwordx2 v[40:41], v[60:61], off offset:512
	v_mul_f32_e32 v54, v23, v94
	v_mul_f32_e32 v55, v23, v92
	v_mul_f32_e32 v56, v23, v96
	v_mul_f32_e32 v57, v23, v98
	v_mul_f32_e32 v54, v68, v54
	v_mul_f32_e32 v55, v69, v55
	v_mul_f32_e32 v56, v70, v56
	v_mul_f32_e32 v57, v71, v57
	v_add_f32_e32 v108, 1.0, v108
	v_add_f32_e32 v109, 1.0, v109
	v_add_f32_e32 v110, 1.0, v110
	v_add_f32_e32 v111, 1.0, v111
	v_fma_f32 v54, v108, v54, v32
	v_fma_f32 v55, v109, v55, v33
	v_fma_f32 v56, v110, v56, v34
	v_fma_f32 v57, v111, v57, v35
	v_cvt_pk_bf16_f32 v58, v54, v55
	v_cvt_pk_bf16_f32 v59, v56, v57
	global_store_dwordx2 v[40:41], v[58:59], off offset:1024
	v_mul_f32_e32 v54, v23, v95
	v_mul_f32_e32 v55, v23, v93
	v_mul_f32_e32 v56, v23, v97
	v_mul_f32_e32 v57, v23, v99
	v_mul_f32_e32 v54, v72, v54
	v_mul_f32_e32 v55, v73, v55
	v_mul_f32_e32 v56, v74, v56
	v_mul_f32_e32 v57, v75, v57
	v_add_f32_e32 v112, 1.0, v112
	v_add_f32_e32 v113, 1.0, v113
	v_add_f32_e32 v114, 1.0, v114
	v_add_f32_e32 v115, 1.0, v115
	v_fma_f32 v54, v112, v54, v36
	v_fma_f32 v55, v113, v55, v37
	v_fma_f32 v56, v114, v56, v38
	v_fma_f32 v57, v115, v57, v39
	v_cvt_pk_bf16_f32 v60, v54, v55
	v_cvt_pk_bf16_f32 v61, v56, v57
	global_store_dwordx2 v[40:41], v[60:61], off offset:1536
	s_mov_b32 s1, s2
	s_cmp_lt_i32 s2, 0x8000
	s_waitcnt vmcnt(4)
	s_cbranch_scc1 .Lfn_D_top
	s_branch .LBB0_934

; DI int otid() { int t = threadIdx.x; asm volatile("" : "+v"(t)); return t; }
; DI int v_st(int k, int c) { const int kk = (k & ~0xC) | ((k & 4) << 1) | ((k & 8) >> 1); return ((kk >> 3) * 4 + (c >> 5)) * 512 + ((kk & 7) * 32 + (c & 31)) * 2; }
; DI int v_rd_base(int lane) { return ((lane & 3) << 3) | (((lane >> 2) & 3) << 6) | (((lane >> 4) & 1) << 5) | (((lane >> 5) & 1) << 8); }
; #define SLOAD(i, k0) do { sr_[i].vs0 = LD8(&Vh[(long)((k0) + sr) * LDK + sc]); sr_[i].vs1 = LD8(&Vh[(long)((k0) + 32 + sr) * LDK + sc]); \
;     sr_[i].ks0 = LD8(&Kh[(long)((k0) + sr) * LDK + sc]); sr_[i].ks1 = LD8(&Kh[(long)((k0) + 32 + sr) * LDK + sc]); } while (0)
; #define SWRITE(b, i) do { *(bf16x8*)((char*)V_lds + (b) * SHM_V + vst0) = sr_[i].vs0;          \
;     *(bf16x8*)((char*)V_lds + (b) * SHM_V + vst1) = sr_[i].vs1; int kc = sc * 2;               \
;     *(bf16x8*)((char*)K_lds + (b) * SHM_K + KSWZ(sr, kc)) = sr_[i].ks0;                       \
;     *(bf16x8*)((char*)K_lds + (b) * SHM_K + KSWZ(32 + sr, kc)) = sr_[i].ks1; } while (0)
; DI void body(const u16* __restrict__ Qb, const u16* __restrict__ Kh, const u16* __restrict__ Vh, u16* __restrict__ Ob, int seq, char* lds) {
;   const int tid = otid(), wid = tid >> 6, lane = tid & 63, r32 = lane & 31, hi = lane >> 5;
;   u16* V_lds = (u16*)lds; u16* K_lds = (u16*)(lds + 2 * SHM_V);
;   float* ws = (float*)(lds + 2 * SHM_V + 2 * SHM_K) + wid * 64; float* li_l = ws; float* al_l = ws + 32;
;   float m_reg = -1e30f, l_reg = 0; f32x16 o[4] = {}; bf16x8 qr[8];
;   const u16* Qw = Qb + (long)(wid * QBLK + r32) * LDQ + hi * 8;
; #pragma unroll
;   for (int d0 = 0; d0 < 8; ++d0) qr[d0] = *reinterpret_cast<const bf16x8*>(Qw + d0 * 16);
;   const int sr = tid >> 4, sc = (tid & 15) * 8, vst0 = v_st(sr, sc), vst1 = v_st(32 + sr, sc);
;   const int vb0 = (int)(uintptr_t)V_lds + v_rd_base(lane);
;   struct { bf16x8 vs0, vs1, ks0, ks1; } sr_[2];
;     ...
;   f32x16 pA0, pA1, pB0, pB1; float mnA, mnB, alA, alB; bf16x8 pa0, pa1, pa2, pa3; const int NT = seq / KVBLK;
;   constexpr int SE = 0, SO = 1;
;   SLOAD(SE, 0); asm volatile("s_waitcnt vmcnt(0)" ::: "memory"); SWRITE(0, SE); __syncthreads();
.LBB0_1150:
	s_lshr_b32 s8, s10, 3
	s_and_b32 s8, s8, 0x1ffff8
	s_add_i32 s8, s8, s60
	s_lshl_b32 s8, s8, 11
	s_and_b32 s70, s8, 0xfffff000
	s_and_b32 s9, s60, 1
	s_ashr_i32 s71, s70, 31
	s_mul_i32 s11, s70, 0xc00
	s_mul_hi_i32 s8, s70, 0xc00
	s_add_u32 s11, s72, s11
	s_addc_u32 s17, s73, s8
	s_lshl_b32 s8, s10, 8
	s_and_b32 s77, s8, 0xf00
	s_mul_i32 s8, s77, 0xc00
	s_add_u32 s8, s11, s8
	s_addc_u32 s19, s17, 0
	s_lshl_b32 s10, s10, 3
	s_lshl_b32 s18, s9, 9
	s_and_b32 s10, s10, 0x180
	s_or_b32 s76, s18, s10
	s_lshl_b32 s10, s76, 1
	s_add_u32 s18, s8, s10
	v_mov_b32_e32 v50, v182
	s_addc_u32 s19, s19, 0
	s_lshl_b32 s10, s9, 8
	s_add_u32 s8, s11, s10
	v_and_b32_e32 v0, 0x3fffffc0, v50
	v_lshl_add_u32 v179, v0, 2, s35
	v_ashrrev_i32_e32 v0, 1, v50
	s_movk_i32 s11, 0xffe0
	v_bfe_u32 v193, v50, 5, 1
	v_and_b32_e32 v178, 0xffffffe0, v0
	v_bfi_b32 v2, s11, v0, v50
	v_mov_b64_e32 v[0:1], s[18:19]
	v_mad_i64_i32 v[0:1], s[18:19], v2, s0, v[0:1]
	v_lshlrev_b32_e32 v176, 4, v193
	v_lshl_add_u64 v[0:1], v[0:1], 0, v[176:177]
	v_ashrrev_i32_e32 v48, 4, v50
	global_load_dwordx4 v[124:127], v[0:1], off
	global_load_dwordx4 v[120:123], v[0:1], off offset:32
	global_load_dwordx4 v[116:119], v[0:1], off offset:64
	global_load_dwordx4 v[112:115], v[0:1], off offset:96
	global_load_dwordx4 v[108:111], v[0:1], off offset:128
	global_load_dwordx4 v[104:107], v[0:1], off offset:160
	global_load_dwordx4 v[100:103], v[0:1], off offset:192
	global_load_dwordx4 v[96:99], v[0:1], off offset:224
	v_and_b32_e32 v1, 0xfffff0, v48
	v_lshlrev_b32_e32 v2, 1, v48
	v_lshlrev_b32_e32 v0, 3, v50
	v_and_or_b32 v1, v2, 8, v1
	v_and_b32_e32 v53, 0x78, v0
	v_lshrrev_b32_e32 v2, 1, v48
	v_lshrrev_b32_e32 v1, 1, v1
	v_bfe_u32 v0, v0, 5, 2
	v_and_b32_e32 v3, 3, v48
	v_or_b32_e32 v1, v1, v0
	v_and_or_b32 v2, v2, 4, v3
	v_lshlrev_b32_e32 v16, 1, v53
	v_lshlrev_b32_e32 v1, 9, v1
	v_lshlrev_b32_e32 v2, 6, v2
	v_and_b32_e32 v3, 48, v16
	v_add_u32_e32 v18, 32, v48
	v_or3_b32 v17, v1, v2, v3
	v_and_b32_e32 v1, 0xfffff0, v18
	v_lshlrev_b32_e32 v4, 1, v18
	v_and_or_b32 v1, v4, 8, v1
	v_lshrrev_b32_e32 v1, 1, v1
	v_or_b32_e32 v0, v1, v0
	v_and_b32_e32 v51, 63, v50
	v_lshlrev_b32_e32 v0, 9, v0
	v_lshlrev_b32_e32 v20, 4, v50
	v_or3_b32 v19, v0, v2, v3
	v_lshlrev_b32_e32 v0, 3, v51
	v_and_b32_e32 v1, 0xc0, v20
	v_lshlrev_b32_e32 v2, 1, v50
	v_and_or_b32 v1, v0, 24, v1
	v_and_b32_e32 v2, 32, v2
	v_and_b32_e32 v0, 0x100, v0
	s_movk_i32 s79, 0x600
	v_or3_b32 v52, v1, v2, v0
	v_mad_i64_i32 v[0:1], s[18:19], v48, s79, 0
	s_addc_u32 s9, s17, 0
	v_or_b32_e32 v0, v0, v53
	v_lshl_add_u64 v[8:9], v[0:1], 1, s[8:9]
	global_load_dwordx4 v[0:3], v[8:9], off offset:2560
	v_mad_i64_i32 v[4:5], s[18:19], v18, s79, 0
	v_or_b32_e32 v4, v4, v53
	v_lshl_add_u64 v[12:13], v[4:5], 1, s[8:9]
	global_load_dwordx4 v[4:7], v[12:13], off offset:2560
	s_nop 0
	v_mov_b32_e32 v80, 0x30000
	v_mov_b32_e32 v81, 0
	v_lshl_add_u64 v[82:83], v[8:9], 0, v[80:81]
	v_lshl_add_u64 v[84:85], v[12:13], 0, v[80:81]
	global_load_dwordx4 v[8:11], v[8:9], off offset:2048
	s_nop 0
	global_load_dwordx4 v[12:15], v[12:13], off offset:2048
	global_load_dwordx4 v[64:67], v[82:83], off offset:2560
	global_load_dwordx4 v[68:71], v[84:85], off offset:2560
	global_load_dwordx4 v[72:75], v[82:83], off offset:2048
	global_load_dwordx4 v[76:79], v[84:85], off offset:2048
	v_add_u32_e32 v195, 16, v17
	s_waitcnt vmcnt(4)
	v_and_b32_e32 v192, 31, v50
	v_lshlrev_b32_e32 v62, 8, v192
	v_and_b32_e32 v63, 0x70, v20
	v_add_u32_e32 v196, 16, v19
	v_or_b32_e32 v54, 32, v176
	v_bitop3_b32 v54, v54, v62, v63 bitop3:0xde
	v_add_u32_e32 v203, 16, v54
	s_cmp_lg_u32 16, -1
	s_cselect_b32 s11, 16, 0
	s_mov_b32 s17, s16
	s_mov_b32 s18, s16
	s_mov_b32 s19, s16
	s_mov_b32 s20, s16
	s_mov_b32 s21, s16
	s_mov_b32 s22, s16
	s_mov_b32 s23, s16
	s_mov_b32 s24, s16
	s_mov_b32 s25, s16
	s_mov_b32 s26, s16
	s_mov_b32 s27, s16
	s_mov_b32 s28, s16
	s_mov_b32 s29, s16
	s_mov_b32 s30, s16
	s_mov_b32 s31, s16
	v_ashrrev_i32_e32 v49, 31, v48
	v_add_u32_e32 v194, s11, v52
	s_mov_b32 s78, 1
	v_lshl_add_u32 v199, v192, 2, v179
	v_mov_b32_e32 v200, 0
	s_waitcnt vmcnt(4)
	ds_write_b128 v195, v[0:3]
	v_lshlrev_b32_e32 v0, 8, v48
	v_and_b32_e32 v1, 0x70, v50
	v_bitop3_b32 v0, v16, v0, v1 bitop3:0xde
	v_add_u32_e32 v197, 16, v0
	v_lshlrev_b32_e32 v0, 8, v18
	v_bitop3_b32 v0, v16, v0, v1 bitop3:0xde
	v_add_u32_e32 v198, 16, v0
	v_bitop3_b32 v0, v176, v62, v63 bitop3:0xde
	v_add_u32_e32 v202, 16, v0
	s_waitcnt vmcnt(4)
	ds_write_b128 v196, v[4:7]
	s_waitcnt vmcnt(4)
	ds_write_b128 v197, v[8:11] offset:32768
	s_waitcnt vmcnt(4)
	ds_write_b128 v198, v[12:15] offset:32768
	s_waitcnt lgkmcnt(0)
	s_barrier
; DI void qkt(f32x16& p0, f32x16& p1, const u16* Ks, const bf16x8* qr, int r32, int hi) {
;   p0 = f32x16{}; p1 = f32x16{};
; #pragma unroll
;   for (int d0 = 0; d0 < 8; ++d0) { int cb = (d0 * 16 + hi * 8) * 2;
;     bf16x8 b0 = *reinterpret_cast<const bf16x8*>((const char*)Ks + KSWZ(r32, cb));
;     bf16x8 b1 = *reinterpret_cast<const bf16x8*>((const char*)Ks + KSWZ(32 + r32, cb));
;     p0 = __builtin_amdgcn_mfma_f32_32x32x16_bf16(b0, qr[d0], p0, 0, 0, 0);
;     p1 = __builtin_amdgcn_mfma_f32_32x32x16_bf16(b1, qr[d0], p1, 0, 0, 0); }
; }
; DI void body(const u16* __restrict__ Qb, const u16* __restrict__ Kh, const u16* __restrict__ Vh, u16* __restrict__ Ob, int seq, char* lds) {
;     ...
;   qkt(pA0, pA1, K_lds, qr, r32, hi); partialSM(pA0, pA1, m_reg, mnA, alA);
	ds_read_b128 v[16:19], v202 offset:32768
	ds_read_b128 v[20:23], v202 offset:40960
	s_waitcnt lgkmcnt(1)
	v_mfma_f32_32x32x16_bf16 v[32:47], v[16:19], v[124:127], 0
	ds_read_b128 v[54:57], v203 offset:32768
	ds_read_b128 v[58:61], v203 offset:40960
	v_mov_b64_e32 v[0:1], s[16:17]
	v_mov_b64_e32 v[2:3], s[18:19]
	v_mov_b64_e32 v[4:5], s[20:21]
	v_mov_b64_e32 v[6:7], s[22:23]
	v_mov_b64_e32 v[8:9], s[24:25]
	v_mov_b64_e32 v[10:11], s[26:27]
	s_waitcnt lgkmcnt(2)
	v_mfma_f32_32x32x16_bf16 v[16:31], v[20:23], v[124:127], 0
	v_mov_b64_e32 v[12:13], s[28:29]
	v_mov_b64_e32 v[14:15], s[30:31]
	s_waitcnt lgkmcnt(1)
	v_mfma_f32_32x32x16_bf16 v[32:47], v[54:57], v[120:123], v[32:47]
	v_or_b32_e32 v54, 64, v176
	v_bitop3_b32 v54, v54, v62, v63 bitop3:0xde
	v_add_u32_e32 v204, 16, v54
	s_waitcnt lgkmcnt(0)
	v_mfma_f32_32x32x16_bf16 v[16:31], v[58:61], v[120:123], v[16:31]
	ds_read_b128 v[54:57], v204 offset:32768
	ds_read_b128 v[58:61], v204 offset:40960
	s_waitcnt lgkmcnt(1)
	v_mfma_f32_32x32x16_bf16 v[32:47], v[54:57], v[116:119], v[32:47]
	v_or_b32_e32 v54, 0x60, v176
	v_bitop3_b32 v54, v54, v62, v63 bitop3:0xde
	v_add_u32_e32 v205, 16, v54
	s_waitcnt lgkmcnt(0)
	v_mfma_f32_32x32x16_bf16 v[16:31], v[58:61], v[116:119], v[16:31]
	ds_read_b128 v[54:57], v205 offset:32768
	ds_read_b128 v[58:61], v205 offset:40960
	s_waitcnt lgkmcnt(1)
	v_mfma_f32_32x32x16_bf16 v[32:47], v[54:57], v[112:115], v[32:47]
	v_or_b32_e32 v54, 0x80, v176
	v_bitop3_b32 v54, v54, v62, v63 bitop3:0xde
	v_add_u32_e32 v206, 16, v54
	s_waitcnt lgkmcnt(0)
	v_mfma_f32_32x32x16_bf16 v[16:31], v[58:61], v[112:115], v[16:31]
	ds_read_b128 v[54:57], v206 offset:32768
	ds_read_b128 v[58:61], v206 offset:40960
	s_waitcnt lgkmcnt(1)
	v_mfma_f32_32x32x16_bf16 v[32:47], v[54:57], v[108:111], v[32:47]
	v_or_b32_e32 v54, 0xa0, v176
	v_bitop3_b32 v54, v54, v62, v63 bitop3:0xde
	v_add_u32_e32 v207, 16, v54
	s_waitcnt lgkmcnt(0)
	v_mfma_f32_32x32x16_bf16 v[16:31], v[58:61], v[108:111], v[16:31]
	ds_read_b128 v[54:57], v207 offset:32768
	ds_read_b128 v[58:61], v207 offset:40960
	s_waitcnt lgkmcnt(1)
	v_mfma_f32_32x32x16_bf16 v[32:47], v[54:57], v[104:107], v[32:47]
	v_or_b32_e32 v54, 0xc0, v176
	v_bitop3_b32 v54, v54, v62, v63 bitop3:0xde
	v_add_u32_e32 v208, 16, v54
	s_waitcnt lgkmcnt(0)
	v_mfma_f32_32x32x16_bf16 v[16:31], v[58:61], v[104:107], v[16:31]
	ds_read_b128 v[54:57], v208 offset:32768
	ds_read_b128 v[58:61], v208 offset:40960
	s_waitcnt lgkmcnt(1)
	v_mfma_f32_32x32x16_bf16 v[32:47], v[54:57], v[100:103], v[32:47]
	v_or_b32_e32 v54, 0xe0, v176
	v_bitop3_b32 v54, v54, v62, v63 bitop3:0xde
	v_add_u32_e32 v209, 16, v54
	s_waitcnt lgkmcnt(0)
	v_mfma_f32_32x32x16_bf16 v[16:31], v[58:61], v[100:103], v[16:31]
	ds_read_b128 v[54:57], v209 offset:32768
	ds_read_b128 v[58:61], v209 offset:40960
	s_waitcnt lgkmcnt(1)
	v_mfma_f32_32x32x16_bf16 v[32:47], v[54:57], v[96:99], v[32:47]
	s_waitcnt lgkmcnt(0)
; #define SLOAD(i, k0) do { sr_[i].vs0 = LD8(&Vh[(long)((k0) + sr) * LDK + sc]); sr_[i].vs1 = LD8(&Vh[(long)((k0) + 32 + sr) * LDK + sc]); \
;     sr_[i].ks0 = LD8(&Kh[(long)((k0) + sr) * LDK + sc]); sr_[i].ks1 = LD8(&Kh[(long)((k0) + 32 + sr) * LDK + sc]); } while (0)
; #define SWRITE(b, i) do { *(bf16x8*)((char*)V_lds + (b) * SHM_V + vst0) = sr_[i].vs0;          \
;     *(bf16x8*)((char*)V_lds + (b) * SHM_V + vst1) = sr_[i].vs1; int kc = sc * 2;               \
;     *(bf16x8*)((char*)K_lds + (b) * SHM_K + KSWZ(sr, kc)) = sr_[i].ks0;                       \
;     *(bf16x8*)((char*)K_lds + (b) * SHM_K + KSWZ(32 + sr, kc)) = sr_[i].ks1; } while (0)
; #define SWAIT() asm volatile("s_waitcnt vmcnt(4)" ::: "memory")
; DI void partialSM(f32x16& p0, f32x16& p1, float& m_reg, float& mn, float& alpha) {
;   constexpr float C = SCALE * 1.4426950408889634f;
;   float pmax = p0[0];
; #pragma unroll
;   for (int r = 1; r < 16; ++r) pmax = fmaxf(pmax, p0[r]);
; #pragma unroll
;   for (int r = 0; r < 16; ++r) pmax = fmaxf(pmax, p1[r]);
;   { auto rr = __builtin_amdgcn_permlane32_swap(__float_as_uint(pmax), __float_as_uint(pmax), false, false);
;     pmax = fmaxf(__uint_as_float(rr[0]), __uint_as_float(rr[1])); }
;   if (__builtin_expect(__all(pmax - m_reg <= THR / SCALE), 1)) { mn = m_reg; alpha = 1.f; }
;   else { mn = fmaxf(m_reg, pmax); alpha = __builtin_amdgcn_exp2f((m_reg - mn) * C); m_reg = mn; }
;   float mnC = -mn * C;
; #pragma unroll
;   for (int r = 0; r < 16; ++r) p0[r] = fmaf(p0[r], C, mnC);
; #pragma unroll
;   for (int r = 0; r < 16; ++r) p1[r] = fmaf(p1[r], C, mnC);
; #pragma unroll
;   for (int r = 0; r < 16; ++r) p0[r] = __builtin_amdgcn_exp2f(p0[r]);
; }
; DI void body(const u16* __restrict__ Qb, const u16* __restrict__ Kh, const u16* __restrict__ Vh, u16* __restrict__ Ob, int seq, char* lds) {
;     ...
;   qkt(pA0, pA1, K_lds, qr, r32, hi); partialSM(pA0, pA1, m_reg, mnA, alA);
;   SLOAD(SO, KVBLK); if (2 < NT) SLOAD(SE, 2 * KVBLK);
;   SWAIT(); SWRITE(1, SO); __syncthreads();
	v_mfma_f32_32x32x16_bf16 v[16:31], v[58:61], v[96:99], v[16:31]
	s_nop 9
	v_max_f32_e32 v54, v33, v33
	v_max_f32_e32 v55, v32, v32
	v_max_f32_e32 v54, v55, v54
	v_max3_f32 v54, v54, v34, v35
	v_max3_f32 v54, v54, v36, v37
	v_max3_f32 v54, v54, v38, v39
	v_max3_f32 v54, v54, v40, v41
	v_max3_f32 v54, v54, v42, v43
	v_max3_f32 v54, v54, v44, v45
	v_max3_f32 v54, v54, v46, v47
	v_max3_f32 v54, v54, v16, v17
	v_max3_f32 v54, v54, v18, v19
	v_max3_f32 v54, v54, v20, v21
	v_max3_f32 v54, v54, v22, v23
	v_max3_f32 v54, v54, v24, v25
	v_max3_f32 v54, v54, v26, v27
	v_max3_f32 v54, v54, v28, v29
	v_max3_f32 v54, v54, v30, v31
	v_mov_b32_e32 v55, v54
	s_nop 1
	v_permlane32_swap_b32_e32 v54, v55
	v_max_f32_e32 v55, v55, v55
	v_max_f32_e32 v54, v54, v54
	v_max_f32_e32 v54, v54, v55
	v_add_f32_e32 v55, 0x7149f2ca, v54
	v_max_f32_e32 v54, 0xf149f2ca, v54
	v_cmp_ge_f32_e32 vcc, s34, v55
	v_sub_f32_e32 v55, 0xf149f2ca, v54
	v_mul_f32_e32 v55, 0x3e0293ee, v55
	s_cmp_eq_u64 vcc, exec
	v_exp_f32_e32 v55, v55
	s_cselect_b64 vcc, -1, 0
	v_cndmask_b32_e32 v164, v54, v191, vcc
	v_mul_f32_e32 v54, 0xbe0293ee, v164
	v_cndmask_b32_e64 v210, v55, 1.0, vcc
	v_mov_b32_e32 v55, v54
	v_fmac_f32_e32 v55, 0x3e0293ee, v47
	v_pk_fma_f32 v[148:149], v[20:21], s[58:59], v[54:55] op_sel_hi:[1,0,0]
	v_pk_fma_f32 v[156:157], v[16:17], s[58:59], v[54:55] op_sel_hi:[1,0,0]
	v_add_u32_e32 v16, 64, v48
	v_add_u32_e32 v20, 0x60, v48
	v_mad_i64_i32 v[16:17], s[18:19], v16, s79, 0
	v_mad_i64_i32 v[20:21], s[18:19], v20, s79, 0
	v_or_b32_e32 v16, v16, v53
	v_or_b32_e32 v20, v20, v53
	v_pk_fma_f32 v[152:153], v[28:29], s[58:59], v[54:55] op_sel_hi:[1,0,0]
	v_pk_fma_f32 v[144:145], v[24:25], s[58:59], v[54:55] op_sel_hi:[1,0,0]
	v_lshl_add_u64 v[24:25], v[16:17], 1, s[8:9]
	v_lshl_add_u64 v[28:29], v[20:21], 1, s[8:9]
	v_fmamk_f32 v32, v32, 0x3e0293ee, v54
	v_fmamk_f32 v34, v34, 0x3e0293ee, v54
	v_pk_fma_f32 v[150:151], v[30:31], s[58:59], v[54:55] op_sel_hi:[1,0,0]
	v_pk_fma_f32 v[158:159], v[26:27], s[58:59], v[54:55] op_sel_hi:[1,0,0]
	v_pk_fma_f32 v[146:147], v[22:23], s[58:59], v[54:55] op_sel_hi:[1,0,0]
	v_pk_fma_f32 v[154:155], v[18:19], s[58:59], v[54:55] op_sel_hi:[1,0,0]
	s_nop 0
	s_nop 0
	v_fmamk_f32 v33, v33, 0x3e0293ee, v54
	v_fmamk_f32 v35, v35, 0x3e0293ee, v54
	v_exp_f32_e32 v175, v32
	v_exp_f32_e32 v161, v34
	v_add_u32_e32 v32, 0xa0, v48
	v_add_u32_e32 v34, 0x80, v48
	v_exp_f32_e32 v214, v33
	v_exp_f32_e32 v213, v35
	v_mad_i64_i32 v[32:33], s[18:19], v32, s79, 0
	v_mad_i64_i32 v[34:35], s[18:19], v34, s79, 0
	v_or_b32_e32 v32, v32, v53
	v_or_b32_e32 v34, v34, v53
	v_lshl_add_u64 v[32:33], v[32:33], 1, s[8:9]
	v_lshl_add_u64 v[34:35], v[34:35], 1, s[8:9]
	global_load_dwordx4 v[128:131], v[32:33], off offset:2048
	global_load_dwordx4 v[132:135], v[34:35], off offset:2048
	global_load_dwordx4 v[136:139], v[32:33], off offset:2560
	global_load_dwordx4 v[140:143], v[34:35], off offset:2560
	s_waitcnt vmcnt(4)
	s_waitcnt vmcnt(7)
	ds_write_b128 v195, v[64:67] offset:16384
	s_waitcnt vmcnt(6)
	ds_write_b128 v196, v[68:71] offset:16384
	s_waitcnt vmcnt(5)
	ds_write_b128 v197, v[72:75] offset:49152
	s_waitcnt vmcnt(4)
	ds_write_b128 v198, v[76:79] offset:49152
	v_lshl_add_u64 v[16:17], v[48:49], 0, s[70:71]
	v_fmamk_f32 v36, v36, 0x3e0293ee, v54
	v_fmamk_f32 v37, v37, 0x3e0293ee, v54
	v_fmamk_f32 v38, v38, 0x3e0293ee, v54
	v_fmamk_f32 v39, v39, 0x3e0293ee, v54
	v_fmamk_f32 v40, v40, 0x3e0293ee, v54
	v_fmamk_f32 v41, v41, 0x3e0293ee, v54
	v_fmamk_f32 v42, v42, 0x3e0293ee, v54
	v_fmamk_f32 v43, v43, 0x3e0293ee, v54
	v_fmamk_f32 v44, v44, 0x3e0293ee, v54
	v_fmamk_f32 v45, v45, 0x3e0293ee, v54
	v_fmamk_f32 v46, v46, 0x3e0293ee, v54
	v_mad_u64_u32 v[18:19], s[18:19], v16, s0, 0
	v_and_b32_e32 v16, 15, v50
	v_exp_f32_e32 v162, v36
	v_exp_f32_e32 v174, v37
	v_exp_f32_e32 v163, v38
	v_exp_f32_e32 v173, v39
	v_exp_f32_e32 v170, v40
	v_exp_f32_e32 v172, v41
	v_exp_f32_e32 v169, v42
	v_exp_f32_e32 v171, v43
	v_exp_f32_e32 v166, v44
	v_exp_f32_e32 v168, v45
	v_exp_f32_e32 v165, v46
	v_exp_f32_e32 v167, v55
	v_lshlrev_b32_e32 v16, 4, v16
	s_addk_i32 s11, 0x4000
	v_mad_i32_i24 v17, v17, s0, v19
	v_or3_b32 v16, v18, s10, v16
	v_cmp_gt_u32_e64 s[8:9], 32, v51
	v_add_u32_e32 v201, s11, v52
	v_lshl_add_u64 v[180:181], s[12:13], 0, v[16:17]
	v_mov_b64_e32 v[62:63], v[14:15]
	v_mov_b64_e32 v[46:47], v[14:15]
	v_mov_b64_e32 v[30:31], v[14:15]
	v_mov_b64_e32 v[60:61], v[12:13]
	v_mov_b64_e32 v[58:59], v[10:11]
	v_mov_b64_e32 v[56:57], v[8:9]
	v_mov_b64_e32 v[54:55], v[6:7]
	v_mov_b64_e32 v[52:53], v[4:5]
	v_mov_b64_e32 v[50:51], v[2:3]
	v_mov_b64_e32 v[48:49], v[0:1]
	v_mov_b64_e32 v[44:45], v[12:13]
	v_mov_b64_e32 v[42:43], v[10:11]
	v_mov_b64_e32 v[40:41], v[8:9]
	v_mov_b64_e32 v[38:39], v[6:7]
	v_mov_b64_e32 v[36:37], v[4:5]
	v_mov_b64_e32 v[34:35], v[2:3]
	v_mov_b64_e32 v[32:33], v[0:1]
	v_mov_b64_e32 v[28:29], v[12:13]
	v_mov_b64_e32 v[26:27], v[10:11]
	v_mov_b64_e32 v[24:25], v[8:9]
	v_mov_b64_e32 v[22:23], v[6:7]
	v_mov_b64_e32 v[20:21], v[4:5]
	v_mov_b64_e32 v[18:19], v[2:3]
	v_mov_b64_e32 v[16:17], v[0:1]
	s_waitcnt lgkmcnt(0)

; DI void st4(u16* p, float a, float b, float c, float d) { u32x2 w = {cvtpk(a, b), cvtpk(c, d)}; *(u32x2*)p = w; }
; #define ROW_LOOP(row, NROWS, BID, NB, WID) \
;   for (int it_ = 0, row = ((NB) == 256 ? ((((BID) & 7)) << 8) + (((BID) >> 3) << 3) + (WID) : (BID) * 8 + (WID)); row < (NROWS); \
;        ++it_, row = ((NB) == 256 ? ((((BID) & 7) + 8 * it_) << 8) + (((BID) >> 3) << 3) + (WID) : (BID) * 8 + (WID) + it_ * (NB) * 8))
; DI float wsum(float v) {
; #pragma unroll
;   for (int o = 32; o; o >>= 1) v += __shfl_xor(v, o);
;   return v;
; }
; template <bool XBF>
; DI void norm_mod_phase(const void* __restrict__ xv, u16* __restrict__ h, const float* __restrict__ gvec, const float* __restrict__ modl, int seq0, int sh_off, int sc_off, int nrows, u16* __restrict__ hdst) {
;     ...
;   ROW_LOOP(row, nrows, bid_, nb_, wid) {
;     const float* mr = modl + (size_t)(seq0 + (row >> 12)) * 6144;
;     f32x4 v[4]; float ss = 0.f;
;     if constexpr (!XBF) {
;       const f32x4* xr = (const f32x4*)((const float*)xv + (size_t)row * 1024);
; #pragma unroll
;       for (int i = 0; i < 4; ++i) v[i] = xr[lane + 64 * i];
;     } else {
;       const u32x2* xr = (const u32x2*)((const u16*)xv + (size_t)row * 1024);
; #pragma unroll
;       for (int i = 0; i < 4; ++i) { const u32x2 w = xr[lane + 64 * i]; v[i] = f32x4{__uint_as_float(w[0] << 16), __uint_as_float(w[0] & 0xffff0000u), __uint_as_float(w[1] << 16), __uint_as_float(w[1] & 0xffff0000u)}; }
;     }
; #pragma unroll
;     for (int i = 0; i < 4; ++i) ss += v[i][0] * v[i][0] + v[i][1] * v[i][1] + v[i][2] * v[i][2] + v[i][3] * v[i][3];
;     ss = wsum(ss);
;     const float rstd = rsqrtf(ss * (1.f / 1024.f) + EPS);
; #pragma unroll
;     for (int i = 0; i < 4; ++i) {
;       const int col = (lane + 64 * i) * 4;
;       const f32x4 g = *(const f32x4*)(gvec + col), sc = *(const f32x4*)(mr + sc_off + col), sh = *(const f32x4*)(mr + sh_off + col);
;       float o[4];
; #pragma unroll
;       for (int q = 0; q < 4; ++q) o[q] = v[i][q] * rstd * g[q] * (1.f + sc[q]) + sh[q];
;       st4(h + (size_t)row * 1024 + col, o[0], o[1], o[2], o[3]);
;     }
.Lfn_B_top:
	v_lshlrev_b32_e32 v86, 16, v76
	v_and_b32_e32 v84, 0xffff0000, v76
	v_lshlrev_b32_e32 v88, 16, v77
	v_and_b32_e32 v90, 0xffff0000, v77
	v_lshlrev_b32_e32 v87, 16, v78
	v_and_b32_e32 v85, 0xffff0000, v78
	v_lshlrev_b32_e32 v89, 16, v79
	v_and_b32_e32 v91, 0xffff0000, v79
	v_lshlrev_b32_e32 v94, 16, v80
	v_and_b32_e32 v92, 0xffff0000, v80
	v_lshlrev_b32_e32 v96, 16, v81
	v_and_b32_e32 v98, 0xffff0000, v81
	v_lshlrev_b32_e32 v95, 16, v82
	v_and_b32_e32 v93, 0xffff0000, v82
	v_lshlrev_b32_e32 v97, 16, v83
	v_and_b32_e32 v99, 0xffff0000, v83
	s_lshr_b32 s28, s24, 12
	s_add_i32 s28, s28, s10
	s_mul_i32 s28, s28, s37
	s_add_u32 s28, s12, s28
	s_addc_u32 s29, s13, 0
	s_add_u32 s28, s28, 0x3000
	s_addc_u32 s29, s29, 0
	global_load_dwordx4 v[100:103], v53, s[28:29]
	global_load_dwordx4 v[104:107], v53, s[28:29] offset:1024
	global_load_dwordx4 v[108:111], v53, s[28:29] offset:2048
	global_load_dwordx4 v[112:115], v53, s[28:29] offset:3072
	global_load_dwordx4 v[24:27], v176, s[28:29]
	global_load_dwordx4 v[28:31], v176, s[28:29] offset:1024
	global_load_dwordx4 v[32:35], v176, s[28:29] offset:2048
	global_load_dwordx4 v[36:39], v176, s[28:29] offset:3072
	s_add_i32 s25, s24, 0x800
	s_cmp_lt_i32 s25, 0x4000
	s_cselect_b32 s22, s25, s24
	s_lshl_b32 s22, s22, 11
	v_lshl_add_u64 v[6:7], v[14:15], 0, s[22:23]
	global_load_dwordx2 v[76:77], v[6:7], off
	global_load_dwordx2 v[78:79], v[6:7], off offset:512
	global_load_dwordx2 v[80:81], v[6:7], off offset:1024
	global_load_dwordx2 v[82:83], v[6:7], off offset:1536
	v_pk_mul_f32 v[42:43], v[84:85], v[84:85]
	v_pk_fma_f32 v[42:43], v[86:87], v[86:87], v[42:43]
	v_pk_fma_f32 v[42:43], v[88:89], v[88:89], v[42:43]
	v_pk_fma_f32 v[42:43], v[90:91], v[90:91], v[42:43]
	v_pk_mul_f32 v[44:45], v[92:93], v[92:93]
	v_pk_fma_f32 v[44:45], v[94:95], v[94:95], v[44:45]
	v_pk_fma_f32 v[44:45], v[96:97], v[96:97], v[44:45]
	v_pk_fma_f32 v[44:45], v[98:99], v[98:99], v[44:45]
	v_add_f32_e32 v21, v42, v43
	v_add_f32_e32 v21, v21, v44
	v_add_f32_e32 v21, v21, v45
	s_lshl_b32 s22, s24, 11
	v_lshl_add_u64 v[40:41], v[16:17], 0, s[22:23]
	s_nop 0
	v_add_f32_dpp v21, v21, v21 row_shr:1 row_mask:0xf bank_mask:0xf bound_ctrl:0
	s_nop 1
	v_add_f32_dpp v21, v21, v21 row_shr:2 row_mask:0xf bank_mask:0xf bound_ctrl:0
	s_nop 1
	v_add_f32_dpp v21, v21, v21 row_shr:4 row_mask:0xf bank_mask:0xf bound_ctrl:0
	s_nop 1
	v_add_f32_dpp v21, v21, v21 row_shr:8 row_mask:0xf bank_mask:0xf bound_ctrl:0
	s_nop 1
	v_add_f32_dpp v21, v21, v21 row_bcast:15 row_mask:0xa bank_mask:0xf
	s_nop 1
	v_add_f32_dpp v21, v21, v21 row_bcast:31 row_mask:0xc bank_mask:0xf
	s_nop 1
	v_readlane_b32 s22, v21, 63
	s_nop 1
	v_mov_b32_e32 v19, s22
	v_fmamk_f32 v19, v19, 0x3a800000, v188
	v_cmp_gt_f32_e32 vcc, 0x800000, v19
	v_mul_f32_e32 v21, 0x4b800000, v19
	s_nop 1
	v_cndmask_b32_e32 v19, v19, v21, vcc
	v_rsq_f32_e32 v19, v19
	s_nop 0
	v_mul_f32_e32 v21, 0x45800000, v19
	v_cndmask_b32_e32 v23, v19, v21, vcc
	s_waitcnt vmcnt(4)
	v_mul_f32_e32 v54, v23, v86
	v_mul_f32_e32 v55, v23, v84
	v_mul_f32_e32 v56, v23, v88
	v_mul_f32_e32 v57, v23, v90
	v_mul_f32_e32 v54, v0, v54
	v_mul_f32_e32 v55, v1, v55
	v_mul_f32_e32 v56, v2, v56
	v_mul_f32_e32 v57, v3, v57
	v_add_f32_e32 v100, 1.0, v100
	v_add_f32_e32 v101, 1.0, v101
	v_add_f32_e32 v102, 1.0, v102
	v_add_f32_e32 v103, 1.0, v103
	v_fma_f32 v54, v100, v54, v24
	v_fma_f32 v55, v101, v55, v25
	v_fma_f32 v56, v102, v56, v26
	v_fma_f32 v57, v103, v57, v27
	v_cvt_pk_bf16_f32 v58, v54, v55
	v_cvt_pk_bf16_f32 v59, v56, v57
	global_store_dwordx2 v[40:41], v[58:59], off
	v_mul_f32_e32 v54, v23, v87
	v_mul_f32_e32 v55, v23, v85
	v_mul_f32_e32 v56, v23, v89
	v_mul_f32_e32 v57, v23, v91
	v_mul_f32_e32 v54, v64, v54
	v_mul_f32_e32 v55, v65, v55
	v_mul_f32_e32 v56, v66, v56
	v_mul_f32_e32 v57, v67, v57
	v_add_f32_e32 v104, 1.0, v104
	v_add_f32_e32 v105, 1.0, v105
	v_add_f32_e32 v106, 1.0, v106
	v_add_f32_e32 v107, 1.0, v107
	v_fma_f32 v54, v104, v54, v28
	v_fma_f32 v55, v105, v55, v29
	v_fma_f32 v56, v106, v56, v30
	v_fma_f32 v57, v107, v57, v31
	v_cvt_pk_bf16_f32 v60, v54, v55
	v_cvt_pk_bf16_f32 v61, v56, v57
	global_store_dwordx2 v[40:41], v[60:61], off offset:512
	v_mul_f32_e32 v54, v23, v94
	v_mul_f32_e32 v55, v23, v92
	v_mul_f32_e32 v56, v23, v96
	v_mul_f32_e32 v57, v23, v98
	v_mul_f32_e32 v54, v68, v54
	v_mul_f32_e32 v55, v69, v55
	v_mul_f32_e32 v56, v70, v56
	v_mul_f32_e32 v57, v71, v57
	v_add_f32_e32 v108, 1.0, v108
	v_add_f32_e32 v109, 1.0, v109
	v_add_f32_e32 v110, 1.0, v110
	v_add_f32_e32 v111, 1.0, v111
	v_fma_f32 v54, v108, v54, v32
	v_fma_f32 v55, v109, v55, v33
	v_fma_f32 v56, v110, v56, v34
	v_fma_f32 v57, v111, v57, v35
	v_cvt_pk_bf16_f32 v58, v54, v55
	v_cvt_pk_bf16_f32 v59, v56, v57
	global_store_dwordx2 v[40:41], v[58:59], off offset:1024
	v_mul_f32_e32 v54, v23, v95
	v_mul_f32_e32 v55, v23, v93
	v_mul_f32_e32 v56, v23, v97
	v_mul_f32_e32 v57, v23, v99
	v_mul_f32_e32 v54, v72, v54
	v_mul_f32_e32 v55, v73, v55
	v_mul_f32_e32 v56, v74, v56
	v_mul_f32_e32 v57, v75, v57
	v_add_f32_e32 v112, 1.0, v112
	v_add_f32_e32 v113, 1.0, v113
	v_add_f32_e32 v114, 1.0, v114
	v_add_f32_e32 v115, 1.0, v115
	v_fma_f32 v54, v112, v54, v36
	v_fma_f32 v55, v113, v55, v37
	v_fma_f32 v56, v114, v56, v38
	v_fma_f32 v57, v115, v57, v39
	v_cvt_pk_bf16_f32 v60, v54, v55
	v_cvt_pk_bf16_f32 v61, v56, v57
	global_store_dwordx2 v[40:41], v[60:61], off offset:1536
	s_mov_b32 s24, s25
	s_cmp_lt_i32 s25, 0x4000
	s_waitcnt vmcnt(4)
	s_cbranch_scc1 .Lfn_B_top
	s_branch .LBB0_1324

; DI void st4(u16* p, float a, float b, float c, float d) { u32x2 w = {cvtpk(a, b), cvtpk(c, d)}; *(u32x2*)p = w; }
; #define ROW_LOOP(row, NROWS, BID, NB, WID) \
;   for (int it_ = 0, row = ((NB) == 256 ? ((((BID) & 7)) << 8) + (((BID) >> 3) << 3) + (WID) : (BID) * 8 + (WID)); row < (NROWS); \
;        ++it_, row = ((NB) == 256 ? ((((BID) & 7) + 8 * it_) << 8) + (((BID) >> 3) << 3) + (WID) : (BID) * 8 + (WID) + it_ * (NB) * 8))
; DI float wsum(float v) {
; #pragma unroll
;   for (int o = 32; o; o >>= 1) v += __shfl_xor(v, o);
;   return v;
; }
; template <bool XBF>
; DI void norm_mod_phase(const void* __restrict__ xv, u16* __restrict__ h, const float* __restrict__ gvec, const float* __restrict__ modl, int seq0, int sh_off, int sc_off, int nrows, u16* __restrict__ hdst) {
;     ...
;   ROW_LOOP(row, nrows, bid_, nb_, wid) {
;     const float* mr = modl + (size_t)(seq0 + (row >> 12)) * 6144;
;     f32x4 v[4]; float ss = 0.f;
;     if constexpr (!XBF) {
;       const f32x4* xr = (const f32x4*)((const float*)xv + (size_t)row * 1024);
; #pragma unroll
;       for (int i = 0; i < 4; ++i) v[i] = xr[lane + 64 * i];
;     } else {
;       const u32x2* xr = (const u32x2*)((const u16*)xv + (size_t)row * 1024);
; #pragma unroll
;       for (int i = 0; i < 4; ++i) { const u32x2 w = xr[lane + 64 * i]; v[i] = f32x4{__uint_as_float(w[0] << 16), __uint_as_float(w[0] & 0xffff0000u), __uint_as_float(w[1] << 16), __uint_as_float(w[1] & 0xffff0000u)}; }
;     }
; #pragma unroll
;     for (int i = 0; i < 4; ++i) ss += v[i][0] * v[i][0] + v[i][1] * v[i][1] + v[i][2] * v[i][2] + v[i][3] * v[i][3];
;     ss = wsum(ss);
;     const float rstd = rsqrtf(ss * (1.f / 1024.f) + EPS);
; #pragma unroll
;     for (int i = 0; i < 4; ++i) {
;       const int col = (lane + 64 * i) * 4;
;       const f32x4 g = *(const f32x4*)(gvec + col), sc = *(const f32x4*)(mr + sc_off + col), sh = *(const f32x4*)(mr + sh_off + col);
;       float o[4];
; #pragma unroll
;       for (int q = 0; q < 4; ++q) o[q] = v[i][q] * rstd * g[q] * (1.f + sc[q]) + sh[q];
;       st4(h + (size_t)row * 1024 + col, o[0], o[1], o[2], o[3]);
;     }
.Lfn_C_top:
	v_lshlrev_b32_e32 v86, 16, v76
	v_and_b32_e32 v84, 0xffff0000, v76
	v_lshlrev_b32_e32 v88, 16, v77
	v_and_b32_e32 v90, 0xffff0000, v77
	v_lshlrev_b32_e32 v87, 16, v78
	v_and_b32_e32 v85, 0xffff0000, v78
	v_lshlrev_b32_e32 v89, 16, v79
	v_and_b32_e32 v91, 0xffff0000, v79
	v_lshlrev_b32_e32 v94, 16, v80
	v_and_b32_e32 v92, 0xffff0000, v80
	v_lshlrev_b32_e32 v96, 16, v81
	v_and_b32_e32 v98, 0xffff0000, v81
	v_lshlrev_b32_e32 v95, 16, v82
	v_and_b32_e32 v93, 0xffff0000, v82
	v_lshlrev_b32_e32 v97, 16, v83
	v_and_b32_e32 v99, 0xffff0000, v83
	s_lshr_b32 s12, s22, 12
	s_add_i32 s12, s12, s17
	s_mul_i32 s12, s12, s37
	s_add_u32 s12, s18, s12
	s_addc_u32 s13, s19, 0
	global_load_dwordx4 v[100:103], v53, s[12:13]
	global_load_dwordx4 v[104:107], v53, s[12:13] offset:1024
	global_load_dwordx4 v[108:111], v53, s[12:13] offset:2048
	global_load_dwordx4 v[112:115], v53, s[12:13] offset:3072
	global_load_dwordx4 v[24:27], v176, s[12:13]
	global_load_dwordx4 v[28:31], v176, s[12:13] offset:1024
	global_load_dwordx4 v[32:35], v176, s[12:13] offset:2048
	global_load_dwordx4 v[36:39], v176, s[12:13] offset:3072
	s_add_i32 s11, s22, 0x800
	s_cmp_lt_i32 s11, 0x8000
	s_cselect_b32 s20, s11, s22
	s_lshl_b32 s20, s20, 11
	v_lshl_add_u64 v[6:7], v[14:15], 0, s[20:21]
	global_load_dwordx2 v[76:77], v[6:7], off
	global_load_dwordx2 v[78:79], v[6:7], off offset:512
	global_load_dwordx2 v[80:81], v[6:7], off offset:1024
	global_load_dwordx2 v[82:83], v[6:7], off offset:1536
	v_pk_mul_f32 v[42:43], v[84:85], v[84:85]
	v_pk_fma_f32 v[42:43], v[86:87], v[86:87], v[42:43]
	v_pk_fma_f32 v[42:43], v[88:89], v[88:89], v[42:43]
	v_pk_fma_f32 v[42:43], v[90:91], v[90:91], v[42:43]
	v_pk_mul_f32 v[44:45], v[92:93], v[92:93]
	v_pk_fma_f32 v[44:45], v[94:95], v[94:95], v[44:45]
	v_pk_fma_f32 v[44:45], v[96:97], v[96:97], v[44:45]
	v_pk_fma_f32 v[44:45], v[98:99], v[98:99], v[44:45]
	v_add_f32_e32 v21, v42, v43
	v_add_f32_e32 v21, v21, v44
	v_add_f32_e32 v21, v21, v45
	s_lshl_b32 s20, s22, 11
	v_lshl_add_u64 v[40:41], v[16:17], 0, s[20:21]
	s_nop 0
	v_add_f32_dpp v21, v21, v21 row_shr:1 row_mask:0xf bank_mask:0xf bound_ctrl:0
	s_nop 1
	v_add_f32_dpp v21, v21, v21 row_shr:2 row_mask:0xf bank_mask:0xf bound_ctrl:0
	s_nop 1
	v_add_f32_dpp v21, v21, v21 row_shr:4 row_mask:0xf bank_mask:0xf bound_ctrl:0
	s_nop 1
	v_add_f32_dpp v21, v21, v21 row_shr:8 row_mask:0xf bank_mask:0xf bound_ctrl:0
	s_nop 1
	v_add_f32_dpp v21, v21, v21 row_bcast:15 row_mask:0xa bank_mask:0xf
	s_nop 1
	v_add_f32_dpp v21, v21, v21 row_bcast:31 row_mask:0xc bank_mask:0xf
	s_nop 1
	v_readlane_b32 s20, v21, 63
	s_nop 1
	v_mov_b32_e32 v19, s20
	v_fmamk_f32 v19, v19, 0x3a800000, v188
	v_cmp_gt_f32_e32 vcc, 0x800000, v19
	v_mul_f32_e32 v21, 0x4b800000, v19
	s_nop 1
	v_cndmask_b32_e32 v19, v19, v21, vcc
	v_rsq_f32_e32 v19, v19
	s_nop 0
	v_mul_f32_e32 v21, 0x45800000, v19
	v_cndmask_b32_e32 v23, v19, v21, vcc
	s_waitcnt vmcnt(4)
	v_mul_f32_e32 v54, v23, v86
	v_mul_f32_e32 v55, v23, v84
	v_mul_f32_e32 v56, v23, v88
	v_mul_f32_e32 v57, v23, v90
	v_mul_f32_e32 v54, v0, v54
	v_mul_f32_e32 v55, v1, v55
	v_mul_f32_e32 v56, v2, v56
	v_mul_f32_e32 v57, v3, v57
	v_add_f32_e32 v100, 1.0, v100
	v_add_f32_e32 v101, 1.0, v101
	v_add_f32_e32 v102, 1.0, v102
	v_add_f32_e32 v103, 1.0, v103
	v_fma_f32 v54, v100, v54, v24
	v_fma_f32 v55, v101, v55, v25
	v_fma_f32 v56, v102, v56, v26
	v_fma_f32 v57, v103, v57, v27
	v_cvt_pk_bf16_f32 v58, v54, v55
	v_cvt_pk_bf16_f32 v59, v56, v57
	global_store_dwordx2 v[40:41], v[58:59], off
	v_mul_f32_e32 v54, v23, v87
	v_mul_f32_e32 v55, v23, v85
	v_mul_f32_e32 v56, v23, v89
	v_mul_f32_e32 v57, v23, v91
	v_mul_f32_e32 v54, v64, v54
	v_mul_f32_e32 v55, v65, v55
	v_mul_f32_e32 v56, v66, v56
	v_mul_f32_e32 v57, v67, v57
	v_add_f32_e32 v104, 1.0, v104
	v_add_f32_e32 v105, 1.0, v105
	v_add_f32_e32 v106, 1.0, v106
	v_add_f32_e32 v107, 1.0, v107
	v_fma_f32 v54, v104, v54, v28
	v_fma_f32 v55, v105, v55, v29
	v_fma_f32 v56, v106, v56, v30
	v_fma_f32 v57, v107, v57, v31
	v_cvt_pk_bf16_f32 v60, v54, v55
	v_cvt_pk_bf16_f32 v61, v56, v57
	global_store_dwordx2 v[40:41], v[60:61], off offset:512
	v_mul_f32_e32 v54, v23, v94
	v_mul_f32_e32 v55, v23, v92
	v_mul_f32_e32 v56, v23, v96
	v_mul_f32_e32 v57, v23, v98
	v_mul_f32_e32 v54, v68, v54
	v_mul_f32_e32 v55, v69, v55
	v_mul_f32_e32 v56, v70, v56
	v_mul_f32_e32 v57, v71, v57
	v_add_f32_e32 v108, 1.0, v108
	v_add_f32_e32 v109, 1.0, v109
	v_add_f32_e32 v110, 1.0, v110
	v_add_f32_e32 v111, 1.0, v111
	v_fma_f32 v54, v108, v54, v32
	v_fma_f32 v55, v109, v55, v33
	v_fma_f32 v56, v110, v56, v34
	v_fma_f32 v57, v111, v57, v35
	v_cvt_pk_bf16_f32 v58, v54, v55
	v_cvt_pk_bf16_f32 v59, v56, v57
	global_store_dwordx2 v[40:41], v[58:59], off offset:1024
	v_mul_f32_e32 v54, v23, v95
	v_mul_f32_e32 v55, v23, v93
	v_mul_f32_e32 v56, v23, v97
	v_mul_f32_e32 v57, v23, v99
	v_mul_f32_e32 v54, v72, v54
	v_mul_f32_e32 v55, v73, v55
	v_mul_f32_e32 v56, v74, v56
	v_mul_f32_e32 v57, v75, v57
	v_add_f32_e32 v112, 1.0, v112
	v_add_f32_e32 v113, 1.0, v113
	v_add_f32_e32 v114, 1.0, v114
	v_add_f32_e32 v115, 1.0, v115
	v_fma_f32 v54, v112, v54, v36
	v_fma_f32 v55, v113, v55, v37
	v_fma_f32 v56, v114, v56, v38
	v_fma_f32 v57, v115, v57, v39
	v_cvt_pk_bf16_f32 v60, v54, v55
	v_cvt_pk_bf16_f32 v61, v56, v57
	global_store_dwordx2 v[40:41], v[60:61], off offset:1536
	s_mov_b32 s22, s11
	s_cmp_lt_i32 s11, 0x8000
	s_waitcnt vmcnt(4)
	s_cbranch_scc1 .Lfn_C_top
	s_branch .LBB0_1515

; #define ROW_LOOP(row, NROWS, BID, NB, WID) \
;   for (int it_ = 0, row = ((NB) == 256 ? ((((BID) & 7)) << 8) + (((BID) >> 3) << 3) + (WID) : (BID) * 8 + (WID)); row < (NROWS); \
;        ++it_, row = ((NB) == 256 ? ((((BID) & 7) + 8 * it_) << 8) + (((BID) >> 3) << 3) + (WID) : (BID) * 8 + (WID) + it_ * (NB) * 8))
; DI void phase_final() {
;     ...
;   ROW_LOOP(row, NSEQ * SEQL, bid, nb, wid) {
;     f32x4* xr = (f32x4*)(out + (size_t)row * 1024);
;     const u32x2* xi = (const u32x2*)(xb + (size_t)row * 1024);
;     f32x4 v[4]; float ss = 0.f;
; #pragma unroll
;     for (int i = 0; i < 4; ++i) { const u32x2 w = xi[lane + 64 * i]; v[i] = f32x4{__uint_as_float(w[0] << 16), __uint_as_float(w[0] & 0xffff0000u), __uint_as_float(w[1] << 16), __uint_as_float(w[1] & 0xffff0000u)};
;       ss += v[i][0] * v[i][0] + v[i][1] * v[i][1] + v[i][2] * v[i][2] + v[i][3] * v[i][3]; }
;     ss = wsum(ss);
;     const float rstd = rsqrtf(ss * (1.f / 1024.f) + EPS);
; #pragma unroll
;     for (int i = 0; i < 4; ++i) {
;       const f32x4 g = *(const f32x4*)(fg + (lane + 64 * i) * 4);
;       f32x4 o; o[0] = v[i][0] * rstd * g[0]; o[1] = v[i][1] * rstd * g[1]; o[2] = v[i][2] * rstd * g[2]; o[3] = v[i][3] * rstd * g[3];
;       xr[lane + 64 * i] = o;
;     }
;   }
.Lff_body:
	v_lshlrev_b32_e32 v90, 16, v80
	v_and_b32_e32 v88, 0xffff0000, v80
	v_lshlrev_b32_e32 v92, 16, v81
	v_and_b32_e32 v94, 0xffff0000, v81
	v_lshlrev_b32_e32 v91, 16, v82
	v_and_b32_e32 v89, 0xffff0000, v82
	v_lshlrev_b32_e32 v93, 16, v83
	v_and_b32_e32 v95, 0xffff0000, v83
	v_lshlrev_b32_e32 v98, 16, v84
	v_and_b32_e32 v96, 0xffff0000, v84
	v_lshlrev_b32_e32 v100, 16, v85
	v_and_b32_e32 v102, 0xffff0000, v85
	v_lshlrev_b32_e32 v99, 16, v86
	v_and_b32_e32 v97, 0xffff0000, v86
	v_lshlrev_b32_e32 v101, 16, v87
	v_and_b32_e32 v103, 0xffff0000, v87
	s_add_i32 s2, s3, 0x800
	s_cmp_lt_i32 s2, 0x18000
	s_cselect_b32 s0, s2, s3
	s_lshl_b32 s0, s0, 11
	v_lshl_add_u64 v[120:121], v[8:9], 0, s[0:1]
	global_load_dwordx2 v[80:81], v[120:121], off
	global_load_dwordx2 v[82:83], v[120:121], off offset:512
	global_load_dwordx2 v[84:85], v[120:121], off offset:1024
	global_load_dwordx2 v[86:87], v[120:121], off offset:1536
	v_pk_mul_f32 v[112:113], v[88:89], v[88:89]
	v_pk_fma_f32 v[112:113], v[90:91], v[90:91], v[112:113]
	v_pk_fma_f32 v[112:113], v[92:93], v[92:93], v[112:113]
	v_pk_fma_f32 v[112:113], v[94:95], v[94:95], v[112:113]
	v_pk_mul_f32 v[114:115], v[96:97], v[96:97]
	v_pk_fma_f32 v[114:115], v[98:99], v[98:99], v[114:115]
	v_pk_fma_f32 v[114:115], v[100:101], v[100:101], v[114:115]
	v_pk_fma_f32 v[114:115], v[102:103], v[102:103], v[114:115]
	v_add_f32_e32 v117, v112, v113
	v_add_f32_e32 v117, v117, v114
	v_add_f32_e32 v117, v117, v115
	s_lshl_b32 s0, s3, 12
	v_lshl_add_u64 v[122:123], v[12:13], 0, s[0:1]
	s_nop 0
	v_add_f32_dpp v117, v117, v117 row_shr:1 row_mask:0xf bank_mask:0xf bound_ctrl:0
	s_nop 1
	v_add_f32_dpp v117, v117, v117 row_shr:2 row_mask:0xf bank_mask:0xf bound_ctrl:0
	s_nop 1
	v_add_f32_dpp v117, v117, v117 row_shr:4 row_mask:0xf bank_mask:0xf bound_ctrl:0
	s_nop 1
	v_add_f32_dpp v117, v117, v117 row_shr:8 row_mask:0xf bank_mask:0xf bound_ctrl:0
	s_nop 1
	v_add_f32_dpp v117, v117, v117 row_bcast:15 row_mask:0xa bank_mask:0xf
	s_nop 1
	v_add_f32_dpp v117, v117, v117 row_bcast:31 row_mask:0xc bank_mask:0xf
	s_nop 1
	v_readlane_b32 s0, v117, 63
	s_nop 1
	v_mov_b32_e32 v116, s0
	v_fmamk_f32 v116, v116, 0x3a800000, v21
	v_mul_f32_e32 v117, 0x4b800000, v116
	v_cmp_gt_f32_e32 vcc, 0x800000, v116
	s_nop 1
	v_cndmask_b32_e32 v116, v116, v117, vcc
	v_rsq_f32_e32 v116, v116
	s_nop 0
	v_mul_f32_e32 v117, 0x45800000, v116
	v_cndmask_b32_e32 v118, v116, v117, vcc
	v_mul_f32_e32 v104, v118, v90
	v_mul_f32_e32 v105, v118, v88
	v_mul_f32_e32 v106, v118, v92
	v_mul_f32_e32 v107, v118, v94
	v_mul_f32_e32 v104, v64, v104
	v_mul_f32_e32 v105, v65, v105
	v_mul_f32_e32 v106, v66, v106
	v_mul_f32_e32 v107, v67, v107
	global_store_dwordx4 v[122:123], v[104:107], off
	v_mul_f32_e32 v108, v118, v91
	v_mul_f32_e32 v109, v118, v89
	v_mul_f32_e32 v110, v118, v93
	v_mul_f32_e32 v111, v118, v95
	v_mul_f32_e32 v108, v68, v108
	v_mul_f32_e32 v109, v69, v109
	v_mul_f32_e32 v110, v70, v110
	v_mul_f32_e32 v111, v71, v111
	global_store_dwordx4 v[122:123], v[108:111], off offset:1024
	v_mul_f32_e32 v104, v118, v98
	v_mul_f32_e32 v105, v118, v96
	v_mul_f32_e32 v106, v118, v100
	v_mul_f32_e32 v107, v118, v102
	v_mul_f32_e32 v104, v72, v104
	v_mul_f32_e32 v105, v73, v105
	v_mul_f32_e32 v106, v74, v106
	v_mul_f32_e32 v107, v75, v107
	global_store_dwordx4 v[122:123], v[104:107], off offset:2048
	v_mul_f32_e32 v108, v118, v99
	v_mul_f32_e32 v109, v118, v97
	v_mul_f32_e32 v110, v118, v101
	v_mul_f32_e32 v111, v118, v103
	v_mul_f32_e32 v108, v76, v108
	v_mul_f32_e32 v109, v77, v109
	v_mul_f32_e32 v110, v78, v110
	v_mul_f32_e32 v111, v79, v111
	global_store_dwordx4 v[122:123], v[108:111], off offset:3072
	s_mov_b32 s3, s2
	s_cmp_lt_i32 s2, 0x18000
	s_cbranch_scc1 .Lff_top
	s_branch .LBB0_1652
